# prep conv_wT: both f32x4 loads of a 64x64 weight tile issued up front (vmcnt 1/0) instead of two serial round trips, in the 5 loops that serialised them; on top of v68
# baseline (speedup 1.0000x reference)
.LBB0_673:
	s_ashr_i32 s23, s20, 31
	s_lshr_b32 s23, s23, 27
	s_add_i32 s23, s20, s23
	s_ashr_i32 s23, s23, 5
	s_lshl_b32 s38, s23, 6
	s_lshl_b32 s23, s23, 11
	v_add_u32_e32 v6, s38, v2
	s_sub_i32 s40, s21, s23
	s_ashr_i32 s41, s40, 31
	v_ashrrev_i32_e32 v7, 31, v6
	v_lshl_add_u64 v[8:9], s[40:41], 2, v[0:1]
	v_lshlrev_b64 v[6:7], 13, v[6:7]
	v_lshl_add_u64 v[10:11], v[8:9], 0, v[6:7]
	global_load_dwordx4 v[6:9], v[10:11], off
	v_add_co_u32_e32 v10, vcc, s87, v10
	s_nop 1
	v_addc_co_u32_e32 v11, vcc, 0, v11, vcc
	global_load_dwordx4 v[10:13], v[10:11], off
	s_waitcnt vmcnt(1)
	v_cvt_pk_bf16_f32 v6, v6, v129
	v_cvt_pk_bf16_f32 v7, v7, v129
	v_cvt_pk_bf16_f32 v8, v8, v129
	v_cvt_pk_bf16_f32 v9, v9, v129
	ds_write_b16 v4, v6
	ds_write_b16 v4, v7 offset:144
	ds_write_b16 v4, v8 offset:288
	ds_write_b16 v4, v9 offset:432
	s_waitcnt vmcnt(0)
	v_cvt_pk_bf16_f32 v6, v10, v129
	v_cvt_pk_bf16_f32 v7, v11, v129
	v_cvt_pk_bf16_f32 v8, v12, v129
	v_cvt_pk_bf16_f32 v9, v13, v129
	ds_write_b16 v4, v6 offset:64
	ds_write_b16 v4, v7 offset:208
	ds_write_b16 v4, v8 offset:352
	ds_write_b16 v4, v9 offset:496
	s_waitcnt lgkmcnt(0)
	s_barrier
	ds_read_b128 v[6:9], v5
	v_mov_b64_e32 v[14:15], s[18:19]
	v_add_u32_e32 v16, s40, v3
	s_ashr_i32 s39, s38, 31
	v_mad_i64_i32 v[14:15], s[40:41], v16, s3, v[14:15]
	s_add_i32 s20, s20, s8
	s_add_i32 s21, s21, s22
	v_lshl_add_u64 v[14:15], s[38:39], 1, v[14:15]
	s_cmpk_lt_i32 s20, 0xb00
	v_lshl_add_u64 v[10:11], v[14:15], 0, v[128:129]
	s_waitcnt lgkmcnt(0)
	global_store_dwordx4 v[10:11], v[6:9], off
	s_barrier
	s_cbranch_scc1 .LBB0_673

.LBB0_679:
	s_ashr_i32 s41, s38, 31
	s_lshr_b32 s41, s41, 27
	s_add_i32 s41, s38, s41
	s_ashr_i32 s41, s41, 5
	s_lshl_b32 s42, s41, 6
	s_lshl_b32 s41, s41, 11
	v_add_u32_e32 v6, s42, v2
	s_sub_i32 s44, s39, s41
	s_ashr_i32 s45, s44, 31
	v_ashrrev_i32_e32 v7, 31, v6
	v_lshl_add_u64 v[8:9], s[44:45], 2, v[0:1]
	v_lshlrev_b64 v[6:7], 13, v[6:7]
	v_lshl_add_u64 v[10:11], v[8:9], 0, v[6:7]
	global_load_dwordx4 v[6:9], v[10:11], off
	v_add_co_u32_e32 v10, vcc, s87, v10
	s_nop 1
	v_addc_co_u32_e32 v11, vcc, 0, v11, vcc
	global_load_dwordx4 v[10:13], v[10:11], off
	s_waitcnt vmcnt(1)
	v_cvt_pk_bf16_f32 v6, v6, v129
	v_cvt_pk_bf16_f32 v7, v7, v129
	v_cvt_pk_bf16_f32 v8, v8, v129
	v_cvt_pk_bf16_f32 v9, v9, v129
	v_add_u32_e32 v14, s44, v3
	ds_write_b16 v4, v6
	ds_write_b16 v4, v7 offset:144
	ds_write_b16 v4, v8 offset:288
	ds_write_b16 v4, v9 offset:432
	s_waitcnt vmcnt(0)
	v_cvt_pk_bf16_f32 v6, v10, v129
	v_cvt_pk_bf16_f32 v7, v11, v129
	v_cvt_pk_bf16_f32 v8, v12, v129
	v_cvt_pk_bf16_f32 v9, v13, v129
	v_ashrrev_i32_e32 v15, 31, v14
	ds_write_b16 v4, v6 offset:64
	ds_write_b16 v4, v7 offset:208
	ds_write_b16 v4, v8 offset:352
	ds_write_b16 v4, v9 offset:496
	s_waitcnt lgkmcnt(0)
	s_barrier
	ds_read_b128 v[6:9], v5
	v_lshlrev_b64 v[14:15], 12, v[14:15]
	s_ashr_i32 s43, s42, 31
	v_lshl_add_u64 v[14:15], s[22:23], 0, v[14:15]
	s_add_i32 s38, s38, s8
	s_add_i32 s39, s39, s40
	v_lshl_add_u64 v[14:15], s[42:43], 1, v[14:15]
	s_cmpk_lt_i32 s38, 0x400
	v_lshl_add_u64 v[10:11], v[14:15], 0, v[128:129]
	s_waitcnt lgkmcnt(0)
	global_store_dwordx4 v[10:11], v[6:9], off
	s_barrier
	s_cbranch_scc1 .LBB0_679

.LBB0_685:
	s_ashr_i32 s38, s37, 31
	s_lshr_b32 s38, s38, 27
	s_add_i32 s38, s37, s38
	s_ashr_i32 s39, s38, 5
	s_lshl_b32 s38, s39, 6
	s_lshl_b32 s39, s39, 11
	v_add_u32_e32 v6, s38, v2
	s_sub_i32 s40, s16, s39
	s_ashr_i32 s41, s40, 31
	v_ashrrev_i32_e32 v7, 31, v6
	v_lshl_add_u64 v[8:9], s[40:41], 2, v[0:1]
	v_lshlrev_b64 v[6:7], 13, v[6:7]
	v_lshl_add_u64 v[10:11], v[8:9], 0, v[6:7]
	global_load_dwordx4 v[6:9], v[10:11], off
	v_add_co_u32_e32 v10, vcc, s87, v10
	s_nop 1
	v_addc_co_u32_e32 v11, vcc, 0, v11, vcc
	global_load_dwordx4 v[10:13], v[10:11], off
	s_waitcnt vmcnt(1)
	v_cvt_pk_bf16_f32 v6, v6, v129
	v_cvt_pk_bf16_f32 v7, v7, v129
	v_cvt_pk_bf16_f32 v8, v8, v129
	v_cvt_pk_bf16_f32 v9, v9, v129
	ds_write_b16 v4, v6
	ds_write_b16 v4, v7 offset:144
	ds_write_b16 v4, v8 offset:288
	ds_write_b16 v4, v9 offset:432
	s_waitcnt vmcnt(0)
	v_cvt_pk_bf16_f32 v6, v10, v129
	v_cvt_pk_bf16_f32 v7, v11, v129
	v_cvt_pk_bf16_f32 v8, v12, v129
	v_cvt_pk_bf16_f32 v9, v13, v129
	ds_write_b16 v4, v6 offset:64
	ds_write_b16 v4, v7 offset:208
	ds_write_b16 v4, v8 offset:352
	ds_write_b16 v4, v9 offset:496
	s_waitcnt lgkmcnt(0)
	s_barrier
	ds_read_b128 v[6:9], v5
	v_mov_b64_e32 v[14:15], s[22:23]
	v_add_u32_e32 v16, s40, v3
	s_ashr_i32 s39, s38, 31
	v_mad_i64_i32 v[14:15], s[40:41], v16, s3, v[14:15]
	s_add_i32 s37, s37, s8
	s_add_i32 s16, s16, s17
	v_lshl_add_u64 v[14:15], s[38:39], 1, v[14:15]
	s_cmpk_lt_i32 s37, 0xb00
	v_lshl_add_u64 v[10:11], v[14:15], 0, v[128:129]
	s_waitcnt lgkmcnt(0)
	global_store_dwordx4 v[10:11], v[6:9], off
	s_barrier
	s_cbranch_scc1 .LBB0_685

.LBB0_688:
	s_ashr_i32 s20, s22, 31
	s_lshr_b32 s20, s20, 27
	s_add_i32 s20, s22, s20
	s_ashr_i32 s21, s20, 5
	s_lshl_b32 s20, s21, 6
	s_lshl_b32 s21, s21, 11
	v_add_u32_e32 v6, s20, v2
	s_sub_i32 s38, s18, s21
	s_ashr_i32 s39, s38, 31
	v_ashrrev_i32_e32 v7, 31, v6
	v_lshl_add_u64 v[8:9], s[38:39], 2, v[0:1]
	v_lshlrev_b64 v[6:7], 13, v[6:7]
	v_lshl_add_u64 v[10:11], v[8:9], 0, v[6:7]
	global_load_dwordx4 v[6:9], v[10:11], off
	v_add_co_u32_e32 v10, vcc, s87, v10
	s_nop 1
	v_addc_co_u32_e32 v11, vcc, 0, v11, vcc
	global_load_dwordx4 v[10:13], v[10:11], off
	s_waitcnt vmcnt(1)
	v_cvt_pk_bf16_f32 v6, v6, v129
	v_cvt_pk_bf16_f32 v7, v7, v129
	v_cvt_pk_bf16_f32 v8, v8, v129
	v_cvt_pk_bf16_f32 v9, v9, v129
	v_add_u32_e32 v14, s38, v3
	ds_write_b16 v4, v6
	ds_write_b16 v4, v7 offset:144
	ds_write_b16 v4, v8 offset:288
	ds_write_b16 v4, v9 offset:432
	s_waitcnt vmcnt(0)
	v_cvt_pk_bf16_f32 v6, v10, v129
	v_cvt_pk_bf16_f32 v7, v11, v129
	v_cvt_pk_bf16_f32 v8, v12, v129
	v_cvt_pk_bf16_f32 v9, v13, v129
	v_ashrrev_i32_e32 v15, 31, v14
	ds_write_b16 v4, v6 offset:64
	ds_write_b16 v4, v7 offset:208
	ds_write_b16 v4, v8 offset:352
	ds_write_b16 v4, v9 offset:496
	s_waitcnt lgkmcnt(0)
	s_barrier
	ds_read_b128 v[6:9], v5
	v_lshlrev_b64 v[14:15], 12, v[14:15]
	s_ashr_i32 s21, s20, 31
	v_lshl_add_u64 v[14:15], s[16:17], 0, v[14:15]
	s_add_i32 s22, s22, s8
	s_add_i32 s18, s18, s19
	v_lshl_add_u64 v[14:15], s[20:21], 1, v[14:15]
	s_cmpk_lt_i32 s22, 0x400
	v_lshl_add_u64 v[10:11], v[14:15], 0, v[128:129]
	s_waitcnt lgkmcnt(0)
	global_store_dwordx4 v[10:11], v[6:9], off
	s_barrier
	s_cbranch_scc1 .LBB0_688

.LBB0_691:
	s_ashr_i32 s19, s18, 31
	s_lshr_b32 s19, s19, 27
	s_add_i32 s19, s18, s19
	s_ashr_i32 s19, s19, 5
	s_lshl_b32 s20, s19, 6
	s_lshl_b32 s19, s19, 11
	v_add_u32_e32 v6, s20, v2
	s_sub_i32 s22, s14, s19
	s_ashr_i32 s23, s22, 31
	v_ashrrev_i32_e32 v7, 31, v6
	v_lshl_add_u64 v[8:9], s[22:23], 2, v[0:1]
	v_lshlrev_b64 v[6:7], 13, v[6:7]
	v_lshl_add_u64 v[10:11], v[8:9], 0, v[6:7]
	global_load_dwordx4 v[6:9], v[10:11], off
	v_add_co_u32_e32 v10, vcc, s87, v10
	s_nop 1
	v_addc_co_u32_e32 v11, vcc, 0, v11, vcc
	global_load_dwordx4 v[10:13], v[10:11], off
	s_waitcnt vmcnt(1)
	v_cvt_pk_bf16_f32 v6, v6, v129
	v_cvt_pk_bf16_f32 v7, v7, v129
	v_cvt_pk_bf16_f32 v8, v8, v129
	v_cvt_pk_bf16_f32 v9, v9, v129
	v_add_u32_e32 v14, s22, v3
	ds_write_b16 v4, v6
	ds_write_b16 v4, v7 offset:144
	ds_write_b16 v4, v8 offset:288
	ds_write_b16 v4, v9 offset:432
	s_waitcnt vmcnt(0)
	v_cvt_pk_bf16_f32 v6, v10, v129
	v_cvt_pk_bf16_f32 v7, v11, v129
	v_cvt_pk_bf16_f32 v8, v12, v129
	v_cvt_pk_bf16_f32 v9, v13, v129
	v_ashrrev_i32_e32 v15, 31, v14
	ds_write_b16 v4, v6 offset:64
	ds_write_b16 v4, v7 offset:208
	ds_write_b16 v4, v8 offset:352
	ds_write_b16 v4, v9 offset:496
	s_waitcnt lgkmcnt(0)
	s_barrier
	ds_read_b128 v[6:9], v5
	v_lshlrev_b64 v[14:15], 9, v[14:15]
	s_ashr_i32 s21, s20, 31
	v_lshl_add_u64 v[14:15], s[16:17], 0, v[14:15]
	s_add_i32 s18, s18, s8
	s_add_i32 s14, s14, s15
	v_lshl_add_u64 v[14:15], s[20:21], 1, v[14:15]
	s_cmpk_lt_i32 s18, 0x80
	v_lshl_add_u64 v[10:11], v[14:15], 0, v[128:129]
	s_waitcnt lgkmcnt(0)
	global_store_dwordx4 v[10:11], v[6:9], off
	s_barrier
	s_cbranch_scc1 .LBB0_691
	s_branch .LBB0_667
